# E3 row loop: the wait for the prefetched row placed per path (vmcnt(8) after the H-row stores, vmcnt(4) on the last-layer path) so it never waits on this row's own stores
# baseline (speedup 1.0000x reference)
.LBB0_326:
	v_mov_b64_e32 v[0:1], v[112:113]
	v_mov_b64_e32 v[2:3], v[114:115]
	v_mov_b64_e32 v[4:5], v[116:117]
	v_mov_b64_e32 v[6:7], v[118:119]
	v_mov_b64_e32 v[12:13], v[50:51]
	v_mul_f32_e32 v40, v13, v13
	v_mov_b64_e32 v[14:15], v[52:53]
	v_fmac_f32_e32 v40, v12, v12
	v_fmac_f32_e32 v40, v14, v14
	v_mov_b64_e32 v[8:9], v[62:63]
	v_fmac_f32_e32 v40, v15, v15
	v_fmac_f32_e32 v40, v8, v8
	v_mov_b64_e32 v[10:11], v[64:65]
	v_fmac_f32_e32 v40, v9, v9
	v_mov_b64_e32 v[94:95], v[68:69]
	v_fmac_f32_e32 v40, v10, v10
	v_mov_b64_e32 v[92:93], v[66:67]
	v_mov_b32_e32 v17, v16
	v_fmac_f32_e32 v40, v11, v11
	v_add_u32_e32 v16, s60, v17
	s_movk_i32 s4, 0x4000
	v_fmac_f32_e32 v40, v92, v92
	v_mov_b64_e32 v[90:91], v[86:87]
	v_pk_mul_f32 v[66:67], v[94:95], v[94:95]
	v_cmp_gt_i32_e32 vcc, s4, v16
	v_fmac_f32_e32 v40, v93, v93
	v_mov_b64_e32 v[88:89], v[84:85]
	v_mov_b64_e32 v[102:103], v[72:73]
	v_cndmask_b32_e32 v50, v17, v16, vcc
	v_add_f32_e32 v17, v66, v40
	v_mov_b64_e32 v[100:101], v[70:71]
	v_pk_mul_f32 v[70:71], v[88:89], v[88:89]
	v_add_f32_e32 v17, v67, v17
	v_add_f32_e32 v17, v70, v17
	v_pk_mul_f32 v[68:69], v[90:91], v[90:91]
	v_add_f32_e32 v17, v71, v17
	v_add_f32_e32 v17, v68, v17
	v_add_f32_e32 v17, v69, v17
	v_mov_b32_e32 v40, 0x358637bd
	v_mov_b64_e32 v[110:111], v[56:57]
	v_add_f32_dpp v17, v17, v17 quad_perm:[1,0,3,2] row_mask:0xf bank_mask:0xf bound_ctrl:1
	v_ashrrev_i32_e32 v51, 31, v50
	v_mov_b64_e32 v[98:99], v[76:77]
	v_add_f32_dpp v17, v17, v17 quad_perm:[2,3,0,1] row_mask:0xf bank_mask:0xf bound_ctrl:1
	v_mov_b64_e32 v[108:109], v[54:55]
	v_lshlrev_b64 v[50:51], 12, v[50:51]
	v_add_f32_dpp v17, v17, v17 row_half_mirror row_mask:0xf bank_mask:0xf bound_ctrl:1
	v_mov_b64_e32 v[96:97], v[74:75]
	v_mov_b64_e32 v[106:107], v[60:61]
	v_add_f32_dpp v17, v17, v17 row_mirror row_mask:0xf bank_mask:0xf bound_ctrl:1
	v_lshl_add_u64 v[72:73], v[18:19], 0, v[50:51]
	v_readlane_b32 s12, v17, 16
	v_readlane_b32 s13, v17, 48
	v_readlane_b32 s4, v17, 0
	v_readlane_b32 s5, v17, 32
	v_mov_b32_e32 v66, s12
	v_mov_b32_e32 v67, s13
	v_pk_add_f32 v[66:67], s[4:5], v[66:67]
	v_lshl_add_u64 v[74:75], v[20:21], 0, v[50:51]
	v_add_f32_e32 v17, v66, v67
	v_fmamk_f32 v17, v17, 0x3a800000, v40
	v_mul_f32_e32 v40, 0x4b800000, v17
	v_cmp_gt_f32_e32 vcc, s70, v17
	v_mov_b64_e32 v[104:105], v[58:59]
	global_load_dwordx4 v[50:53], v[72:73], off
	global_load_dwordx4 v[62:65], v[72:73], off offset:1024
	global_load_dwordx4 v[54:57], v[74:75], off
	global_load_dwordx4 v[58:61], v[74:75], off offset:1024
	v_cndmask_b32_e32 v17, v17, v40, vcc
	v_rsq_f32_e32 v17, v17
	global_load_dwordx4 v[66:69], v[72:73], off offset:2048
	global_load_dwordx4 v[84:87], v[72:73], off offset:3072
	s_nop 0
	global_load_dwordx4 v[70:73], v[74:75], off offset:2048
	s_nop 0
	global_load_dwordx4 v[74:77], v[74:75], off offset:3072
	v_cmp_lt_i32_e64 s[4:5], s66, v16
	v_mul_f32_e32 v40, 0x45800000, v17
	v_cndmask_b32_e32 v40, v17, v40, vcc
	v_pk_mul_f32 v[12:13], v[12:13], v[40:41] op_sel_hi:[1,0]
	v_pk_mul_f32 v[14:15], v[14:15], v[40:41] op_sel_hi:[1,0]
	v_pk_mul_f32 v[8:9], v[8:9], v[40:41] op_sel_hi:[1,0]
	v_pk_mul_f32 v[10:11], v[10:11], v[40:41] op_sel_hi:[1,0]
	v_pk_mul_f32 v[78:79], v[92:93], v[40:41] op_sel_hi:[1,0]
	v_pk_mul_f32 v[92:93], v[94:95], v[40:41] op_sel_hi:[1,0]
	s_andn2_b64 vcc, exec, s[8:9]
	v_pk_mul_f32 v[0:1], v[0:1], v[12:13]
	v_pk_mul_f32 v[2:3], v[2:3], v[14:15]
	v_pk_fma_f32 v[12:13], v[4:5], v[0:1], v[108:109]
	v_pk_fma_f32 v[14:15], v[6:7], v[2:3], v[110:111]
	global_store_dwordx4 v[48:49], v[12:15], off
	s_nop 0
	v_mov_b64_e32 v[0:1], v[120:121]
	v_mov_b64_e32 v[2:3], v[122:123]
	v_mov_b64_e32 v[4:5], v[124:125]
	v_mov_b64_e32 v[6:7], v[126:127]
	v_pk_mul_f32 v[0:1], v[0:1], v[8:9]
	v_pk_mul_f32 v[2:3], v[2:3], v[10:11]
	v_pk_fma_f32 v[8:9], v[4:5], v[0:1], v[104:105]
	v_pk_fma_f32 v[10:11], v[6:7], v[2:3], v[106:107]
	global_store_dwordx4 v[48:49], v[8:11], off offset:1024
	s_nop 0
	v_mov_b64_e32 v[0:1], v[128:129]
	v_mov_b64_e32 v[2:3], v[130:131]
	v_mov_b64_e32 v[4:5], v[132:133]
	v_mov_b64_e32 v[6:7], v[134:135]
	v_pk_mul_f32 v[0:1], v[0:1], v[78:79]
	v_pk_mul_f32 v[2:3], v[2:3], v[92:93]
	v_pk_fma_f32 v[4:5], v[4:5], v[0:1], v[100:101]
	v_pk_fma_f32 v[6:7], v[6:7], v[2:3], v[102:103]
	global_store_dwordx4 v[48:49], v[4:7], off offset:2048
	s_nop 0
	v_mov_b64_e32 v[0:1], v[136:137]
	v_mov_b64_e32 v[2:3], v[138:139]
	v_mov_b64_e32 v[92:93], v[140:141]
	v_mov_b64_e32 v[94:95], v[142:143]
	v_pk_mul_f32 v[78:79], v[88:89], v[40:41] op_sel_hi:[1,0]
	v_pk_mul_f32 v[88:89], v[90:91], v[40:41] op_sel_hi:[1,0]
	v_pk_mul_f32 v[0:1], v[78:79], v[0:1]
	v_pk_mul_f32 v[2:3], v[88:89], v[2:3]
	v_pk_fma_f32 v[0:1], v[92:93], v[0:1], v[96:97]
	v_pk_fma_f32 v[2:3], v[94:95], v[2:3], v[98:99]
	global_store_dwordx4 v[48:49], v[0:3], off offset:3072
	s_cbranch_vccnz .Le3_last
	v_pk_mul_f32 v[78:79], v[12:13], v[12:13]
	v_pk_mul_f32 v[88:89], v[14:15], v[14:15]
	v_add_f32_e32 v17, v78, v79
	v_add_f32_e32 v17, v88, v17
	v_pk_mul_f32 v[90:91], v[8:9], v[8:9]
	v_add_f32_e32 v17, v89, v17
	v_add_f32_e32 v17, v90, v17
	v_pk_mul_f32 v[92:93], v[10:11], v[10:11]
	v_add_f32_e32 v17, v91, v17
	v_add_f32_e32 v17, v92, v17
	v_pk_mul_f32 v[94:95], v[4:5], v[4:5]
	v_add_f32_e32 v17, v93, v17
	v_add_f32_e32 v17, v94, v17
	v_pk_mul_f32 v[96:97], v[6:7], v[6:7]
	v_add_f32_e32 v17, v95, v17
	v_add_f32_e32 v17, v96, v17
	v_pk_mul_f32 v[98:99], v[0:1], v[0:1]
	v_add_f32_e32 v17, v97, v17
	v_add_f32_e32 v17, v98, v17
	v_add_f32_e32 v17, v99, v17
	v_mov_b64_e32 v[88:89], v[144:145]
	v_mov_b64_e32 v[90:91], v[146:147]
	v_mov_b64_e32 v[92:93], v[148:149]
	v_mov_b64_e32 v[94:95], v[150:151]
	v_mov_b64_e32 v[96:97], v[152:153]
	v_mov_b64_e32 v[98:99], v[154:155]
	v_pk_mul_f32 v[100:101], v[2:3], v[2:3]
	v_mov_b32_e32 v40, 0x358637bd
	v_add_f32_e32 v17, v100, v17
	v_add_f32_e32 v17, v101, v17
	s_nop 1
	v_add_f32_dpp v17, v17, v17 quad_perm:[1,0,3,2] row_mask:0xf bank_mask:0xf bound_ctrl:1
	s_nop 1
	v_add_f32_dpp v17, v17, v17 quad_perm:[2,3,0,1] row_mask:0xf bank_mask:0xf bound_ctrl:1
	s_nop 1
	v_add_f32_dpp v17, v17, v17 row_half_mirror row_mask:0xf bank_mask:0xf bound_ctrl:1
	s_nop 1
	v_add_f32_dpp v17, v17, v17 row_mirror row_mask:0xf bank_mask:0xf bound_ctrl:1
	s_nop 0
	v_readlane_b32 s14, v17, 16
	v_readlane_b32 s15, v17, 48
	v_readlane_b32 s12, v17, 0
	v_readlane_b32 s13, v17, 32
	v_mov_b32_e32 v78, s14
	v_mov_b32_e32 v79, s15
	v_pk_add_f32 v[78:79], s[12:13], v[78:79]
	s_nop 0
	v_add_f32_e32 v17, v78, v79
	v_fmamk_f32 v17, v17, 0x3a800000, v40
	v_cmp_gt_f32_e32 vcc, s70, v17
	v_mul_f32_e32 v40, 0x4b800000, v17
	v_pk_add_f32 v[78:79], v[96:97], 1.0 op_sel_hi:[1,0]
	v_cndmask_b32_e32 v17, v17, v40, vcc
	v_rsq_f32_e32 v17, v17
	s_nop 0
	v_mul_f32_e32 v40, 0x45800000, v17
	v_cndmask_b32_e32 v40, v17, v40, vcc
	v_pk_mul_f32 v[12:13], v[12:13], v[40:41] op_sel_hi:[1,0]
	v_pk_mul_f32 v[14:15], v[14:15], v[40:41] op_sel_hi:[1,0]
	v_pk_mul_f32 v[12:13], v[88:89], v[12:13]
	v_pk_mul_f32 v[14:15], v[90:91], v[14:15]
	v_pk_fma_f32 v[12:13], v[78:79], v[12:13], v[92:93]
	v_pk_add_f32 v[78:79], v[98:99], 1.0 op_sel_hi:[1,0]
	v_cvt_pk_f16_f32 v12, v12, v13
	v_pk_fma_f32 v[14:15], v[78:79], v[14:15], v[94:95]
	v_pk_mul_f32 v[8:9], v[8:9], v[40:41] op_sel_hi:[1,0]
	v_cvt_pk_f16_f32 v13, v14, v15
	global_store_dwordx2 v[46:47], v[12:13], off
	s_nop 0
	v_mov_b64_e32 v[12:13], v[156:157]
	v_mov_b64_e32 v[14:15], v[158:159]
	s_nop 0
	v_mov_b64_e32 v[88:89], v[160:161]
	v_mov_b64_e32 v[90:91], v[162:163]
	v_mov_b64_e32 v[92:93], v[164:165]
	v_mov_b64_e32 v[94:95], v[166:167]
	v_pk_mul_f32 v[10:11], v[10:11], v[40:41] op_sel_hi:[1,0]
	v_pk_mul_f32 v[4:5], v[4:5], v[40:41] op_sel_hi:[1,0]
	v_pk_mul_f32 v[6:7], v[6:7], v[40:41] op_sel_hi:[1,0]
	v_pk_mul_f32 v[0:1], v[0:1], v[40:41] op_sel_hi:[1,0]
	v_pk_mul_f32 v[2:3], v[2:3], v[40:41] op_sel_hi:[1,0]
	v_pk_mul_f32 v[8:9], v[12:13], v[8:9]
	v_pk_mul_f32 v[10:11], v[14:15], v[10:11]
	v_pk_add_f32 v[12:13], v[92:93], 1.0 op_sel_hi:[1,0]
	s_nop 0
	v_pk_fma_f32 v[8:9], v[12:13], v[8:9], v[88:89]
	v_pk_add_f32 v[12:13], v[94:95], 1.0 op_sel_hi:[1,0]
	v_cvt_pk_f16_f32 v8, v8, v9
	v_pk_fma_f32 v[10:11], v[12:13], v[10:11], v[90:91]
	s_nop 0
	v_cvt_pk_f16_f32 v9, v10, v11
	global_store_dwordx2 v[46:47], v[8:9], off offset:512
	s_nop 0
	v_mov_b64_e32 v[8:9], v[168:169]
	v_mov_b64_e32 v[10:11], v[170:171]
	s_nop 0
	v_mov_b64_e32 v[12:13], v[172:173]
	v_mov_b64_e32 v[14:15], v[174:175]
	v_mov_b64_e32 v[88:89], v[176:177]
	v_mov_b64_e32 v[90:91], v[178:179]
	v_pk_mul_f32 v[4:5], v[8:9], v[4:5]
	v_pk_mul_f32 v[6:7], v[10:11], v[6:7]
	v_pk_add_f32 v[8:9], v[88:89], 1.0 op_sel_hi:[1,0]
	s_nop 0
	v_pk_fma_f32 v[4:5], v[4:5], v[8:9], v[12:13]
	v_pk_add_f32 v[8:9], v[90:91], 1.0 op_sel_hi:[1,0]
	v_cvt_pk_f16_f32 v4, v4, v5
	v_pk_fma_f32 v[6:7], v[6:7], v[8:9], v[14:15]
	s_nop 0
	v_cvt_pk_f16_f32 v5, v6, v7
	global_store_dwordx2 v[46:47], v[4:5], off offset:1024
	s_nop 0
	v_mov_b64_e32 v[8:9], v[180:181]
	v_mov_b64_e32 v[10:11], v[182:183]
	s_nop 0
	v_mov_b64_e32 v[4:5], v[184:185]
	v_mov_b64_e32 v[6:7], v[186:187]
	v_mov_b64_e32 v[12:13], v[188:189]
	v_mov_b64_e32 v[14:15], v[190:191]
	v_pk_mul_f32 v[0:1], v[0:1], v[8:9]
	v_pk_mul_f32 v[2:3], v[2:3], v[10:11]
	v_pk_add_f32 v[8:9], v[12:13], 1.0 op_sel_hi:[1,0]
	s_nop 0
	v_pk_fma_f32 v[0:1], v[0:1], v[8:9], v[4:5]
	v_pk_add_f32 v[4:5], v[14:15], 1.0 op_sel_hi:[1,0]
	v_cvt_pk_f16_f32 v0, v0, v1
	v_pk_fma_f32 v[2:3], v[2:3], v[4:5], v[6:7]
	s_nop 0
	v_cvt_pk_f16_f32 v1, v2, v3
	global_store_dwordx2 v[46:47], v[0:1], off offset:1536
	s_waitcnt vmcnt(8)
	s_branch .LBB0_325
.Le3_last:
	s_waitcnt vmcnt(4)
	s_branch .LBB0_325
